# attn64 prompt units mapped one (batch,head) per XCD, on top of the K swizzle change
# baseline (speedup 1.0000x reference)
.LBB0_912:
	s_mul_hi_i32 s0, s48, 0x66666667
	s_lshr_b32 s1, s0, 31
	s_ashr_i32 s0, s0, 9
	s_add_i32 s0, s0, s1
	s_mulk_i32 s0, 0x500
	s_sub_i32 s6, s48, s0
	s_and_b32 s0, s6, 31
	s_xor_b32 s1, s0, 63
	s_bitcmp1_b32 s6, 8
	s_cselect_b32 s0, s1, s0
.LBB0_918:
	flat_load_dword v200, v[198:199]
	s_cmpk_lt_i32 s6, 0x400
	s_cselect_b64 s[18:19], -1, 0
	s_lshr_b32 s1, s6, 5
	s_cmpk_gt_i32 s6, 0x3ff
	s_cselect_b64 s[4:5], -1, 0
	s_and_b64 s[10:11], s[4:5], exec
	s_cselect_b32 s1, s6, s1
	v_mov_b32_e32 v4, v0
	s_movk_i32 s10, 0x140
	s_and_b32 s1, s1, 7
	s_waitcnt vmcnt(0) lgkmcnt(0)
	s_barrier
	s_nop 0
	v_cmp_gt_i32_e32 vcc, s10, v4
	s_and_saveexec_b64 s[20:21], vcc
	s_cbranch_execz .LBB0_920
	s_mul_i32 s10, s1, 0x500
	v_readlane_b32 s11, v244, 18
	s_add_u32 s10, s11, s10
	v_readlane_b32 s11, v244, 55
	s_addc_u32 s11, s11, 0
	v_ashrrev_i32_e32 v5, 31, v4
	v_lshl_add_u64 v[6:7], v[4:5], 2, s[10:11]
	flat_load_dword v3, v[6:7]
	v_lshl_add_u32 v4, v4, 2, 0
	v_add_u32_e32 v4, 0x1c800, v4
	s_waitcnt vmcnt(0) lgkmcnt(0)
	ds_write_b32 v4, v3
.LBB0_920:
	s_or_b64 exec, exec, s[20:21]
	s_lshr_b32 s12, s6, 9
	s_and_b32 s6, s6, 0xff
	s_lshr_b32 vcc_lo, s6, 3
	s_and_b64 s[10:11], s[4:5], exec
	s_cselect_b32 s12, vcc_lo, s12
	s_andn2_b64 vcc, exec, s[18:19]
	s_mov_b64 s[20:21], -1
	s_waitcnt lgkmcnt(0)
	s_barrier
	s_cbranch_vccnz .LBB0_922
	s_lshl_b32 s10, s0, 8
	s_lshl_b32 s6, s12, 14
	s_add_i32 s11, s74, s10
	s_add_i32 s13, s11, s6
	s_lshl_b32 s10, s12, 25
	v_readlane_b32 s6, v244, 56
	s_add_u32 s14, s6, s10
	v_readlane_b32 s6, v244, 57
	s_addc_u32 s15, s6, 0
	s_lshl_b32 s6, s1, 7
	s_mov_b64 s[18:19], s[6:7]
	s_lshl_b32 s6, s1, 8
	s_add_u32 s44, s14, s6
	s_addc_u32 s45, s15, 0
	s_add_u32 s10, s85, s10
	s_addc_u32 s14, s86, 0
	s_add_u32 s52, s10, s6
	s_addc_u32 s53, s14, 0
	s_lshl_b32 s0, s0, 2
	s_add_i32 s50, s0, 4
	s_or_b32 s49, s0, 3
	s_add_i32 s10, s0, s75
	s_sub_i32 s11, 0, s11
	s_mov_b64 s[20:21], 0
	s_mov_b32 s6, s13
